# gla_m1: all table loads (low-rank u, w_up, b_up) plus k-row and v-row loads issued together at job start, later waits that also stalled on bcb stores removed
# baseline (speedup 1.0000x reference)
.LBB0_351:
	s_andn2_b64 vcc, exec, s[0:1]
	s_cbranch_vccnz .LBB0_380
	s_add_i32 s4, s94, 0xfffffc00
	v_mov_b32_e32 v22, v180
	s_lshl_b32 s0, s4, 3
	v_mov_b32_e32 v0, v180
	s_and_b32 s8, s94, 7
	s_and_b32 s9, s0, 0x7fffffc0
	s_nop 0
	v_cmp_gt_i32_e32 vcc, s21, v0
	v_and_b32_e32 v6, 63, v0
	s_and_saveexec_b64 s[0:1], vcc
	s_cbranch_execz .LBB0_364
	v_lshl_add_u32 v1, v0, 2, 0
	v_readlane_b32 s6, v254, 18
	v_readlane_b32 s7, v254, 19
	v_lshrrev_b32_e32 v2, 5, v0
	v_add_u32_e32 v2, s9, v2
	v_and_b32_e32 v7, 31, v0
	v_mov_b64_e32 v[4:5], s[6:7]
	v_mad_i64_i32 v[8:9], s[12:13], v2, s77, v[4:5]
	v_lshlrev_b32_e32 v10, 1, v7
	v_add_u32_e32 v10, 0x5000, v10
	v_mov_b32_e32 v11, 0
	s_mov_b32 s10, 0x50400
	s_mov_b32 s11, 0
	v_lshl_add_u64 v[8:9], v[8:9], 0, v[10:11]
	global_load_ushort v12, v[8:9], off
	v_lshl_add_u64 v[8:9], v[8:9], 0, s[10:11]
	global_load_ushort v13, v[8:9], off
	v_lshl_add_u64 v[8:9], v[8:9], 0, s[10:11]
	global_load_ushort v14, v[8:9], off
	v_lshl_add_u64 v[8:9], v[8:9], 0, s[10:11]
	global_load_ushort v15, v[8:9], off
	v_lshrrev_b32_e32 v16, 6, v0
	v_lshlrev_b32_e32 v2, 9, v16
	v_lshlrev_b32_e32 v16, 11, v16
	v_lshl_add_u32 v16, v6, 2, v16
	s_lshl_b32 s12, s8, 8
	v_add_u32_e32 v16, s12, v16
	global_load_dword v18, v16, s[26:27]
	v_add_u32_e32 v17, 0x4000, v16
	global_load_dword v19, v17, s[26:27]
	v_add_u32_e32 v17, 0x8000, v16
	global_load_dword v20, v17, s[26:27]
	v_add_u32_e32 v17, 0xc000, v16
	global_load_dword v21, v17, s[26:27]
	v_lshrrev_b32_e32 v26, 3, v0
	v_add_u32_e32 v26, s9, v26
	v_mad_i64_i32 v[24:25], s[12:13], v26, s77, v[4:5]
	v_and_b32_e32 v27, 7, v0
	v_lshlrev_b32_e32 v28, 4, v27
	s_lshl_b32 s12, s8, 7
	v_add_u32_e32 v28, s12, v28
	v_add_u32_e32 v28, 0x1400, v28
	v_mov_b32_e32 v29, 0
	v_lshl_add_u64 v[30:31], v[24:25], 0, v[28:29]
	global_load_dwordx4 v[212:215], v[30:31], off
	v_lshlrev_b32_e32 v28, 5, v27
	s_lshl_b32 s12, s8, 8
	v_add_u32_e32 v28, s12, v28
	v_add_u32_e32 v28, 0x1800, v28
	v_lshl_add_u64 v[30:31], v[24:25], 0, v[28:29]
	global_load_dwordx4 v[216:219], v[30:31], off
	global_load_dwordx4 v[220:223], v[30:31], off offset:16
	s_lshl_b32 s12, s8, 6
	v_or3_b32 v2, v2, s12, v6
	s_movk_i32 s12, 0x80
	v_cmp_gt_u32_e64 s[12:13], s12, v0
	v_lshlrev_b32_e32 v2, 2, v2
	s_nop 1
	v_cndmask_b32_e64 v2, 0, v2, s[12:13]
	global_load_dword v3, v2, s[28:29]
	s_waitcnt vmcnt(0)
	v_lshlrev_b32_e32 v12, 16, v12
	v_lshlrev_b32_e32 v13, 16, v13
	v_lshlrev_b32_e32 v14, 16, v14
	v_lshlrev_b32_e32 v15, 16, v15
	ds_write2st64_b32 v1, v12, v13 offset1:8
	ds_write2st64_b32 v1, v14, v15 offset0:16 offset1:24
	ds_write2st64_b32 v1, v18, v19 offset0:32 offset1:40
	ds_write2st64_b32 v1, v20, v21 offset0:48 offset1:56
	s_and_saveexec_b64 s[2:3], s[12:13]
	ds_write_b32 v1, v3 offset:16384
	s_mov_b64 exec, s[2:3]

.LBB0_377:
	s_or_b64 exec, exec, s[0:1]
	v_readlane_b32 s52, v254, 12
	v_ashrrev_i32_e32 v3, 3, v22
	v_readlane_b32 s58, v254, 18
	v_readlane_b32 s59, v254, 19
	v_add_u32_e32 v4, s9, v3
	v_and_b32_e32 v12, 7, v22
	v_mov_b64_e32 v[0:1], s[58:59]
	v_mad_i64_i32 v[0:1], s[0:1], v4, s77, v[0:1]
	s_lshl_b32 s24, s8, 7
	v_lshl_add_u64 v[4:5], v[0:1], 0, s[24:25]
	v_lshlrev_b32_e32 v112, 4, v12
	v_lshl_add_u64 v[4:5], v[4:5], 0, v[112:113]
	v_add_co_u32_e32 v4, vcc, 0x1000, v4
	v_lshlrev_b32_e32 v112, 5, v12
	s_nop 0
	v_addc_co_u32_e32 v5, vcc, 0, v5, vcc
	v_mov_b32_e32 v4, v212
	v_mov_b32_e32 v5, v213
	v_mov_b32_e32 v6, v214
	v_mov_b32_e32 v7, v215
	v_add_u32_e32 v8, 0, v112
	v_mad_u64_u32 v[10:11], s[0:1], v3, s11, v[8:9]
	ds_read_b32 v9, v8 offset:33788
	ds_read_b32 v11, v10 offset:17408
	v_lshlrev_b32_e32 v3, 1, v3
	v_mul_u32_u24_e32 v15, 0x240, v12
	v_add_u32_e32 v16, 0, v3
	s_movk_i32 s0, 0x460
	s_waitcnt lgkmcnt(0)
	v_sub_f32_e32 v9, v9, v11
	v_mul_f32_e32 v9, 0x3fb8aa3b, v9
	v_exp_f32_e32 v9, v9
	v_lshl_add_u32 v15, v15, 1, v16
	s_lshl_b32 s24, s8, 8
	v_lshl_add_u64 v[0:1], v[0:1], 0, s[24:25]
	v_lshl_add_u64 v[0:1], v[0:1], 0, v[112:113]
	v_readlane_b32 s53, v254, 13
	v_readlane_b32 s54, v254, 14
	v_readlane_b32 s55, v254, 15
	v_readlane_b32 s56, v254, 16
	v_readlane_b32 s57, v254, 17
	v_readlane_b32 s60, v254, 20
	v_readlane_b32 s61, v254, 21
	v_readlane_b32 s62, v254, 22
	v_readlane_b32 s63, v254, 23
	v_readlane_b32 s64, v254, 24
	v_readlane_b32 s65, v254, 25
	v_readlane_b32 s66, v254, 26
	v_readlane_b32 s67, v254, 27
	s_nop 0
	v_lshlrev_b32_e32 v11, 16, v4
	v_mul_f32_e32 v9, v9, v11
	v_cvt_pk_bf16_f32 v9, v9, v113
	ds_read_b32 v13, v8 offset:34048
	ds_read_b32 v14, v10 offset:34048
	v_mad_u32_u24 v8, v12, s0, v8
	s_movk_i32 s0, 0xfba0
	ds_write_b16 v15, v9 offset:50688
	v_and_b32_e32 v4, 0xffff0000, v4
	s_waitcnt lgkmcnt(1)
	v_sub_f32_e32 v13, v13, v14
	v_mul_f32_e32 v13, 0x3fb8aa3b, v13
	v_exp_f32_e32 v13, v13
	v_mad_i32_i24 v14, v12, s0, v8
	v_add_u32_e32 v8, v8, v3
	s_mov_b64 s[0:1], 0x1800
	v_mul_f32_e32 v9, v13, v11
	v_cvt_pk_bf16_f32 v9, v9, v113
	ds_read_b32 v11, v14 offset:33792
	ds_read_b32 v13, v10 offset:17412
	ds_write_b16 v8, v9 offset:59904
	s_waitcnt lgkmcnt(1)
	v_sub_f32_e32 v11, v11, v13
	v_mul_f32_e32 v11, 0x3fb8aa3b, v11
	v_exp_f32_e32 v11, v11
	v_lshl_or_b32 v13, v12, 3, 1
	v_mul_u32_u24_e32 v13, 0x48, v13
	v_mul_f32_e32 v8, v11, v4
	v_cvt_pk_bf16_f32 v8, v8, v113
	ds_read_b32 v9, v14 offset:34052
	ds_read_b32 v11, v10 offset:34052
	s_waitcnt lgkmcnt(0)
	v_sub_f32_e32 v9, v9, v11
	v_mul_f32_e32 v9, 0x3fb8aa3b, v9
	v_exp_f32_e32 v9, v9
	v_lshlrev_b32_e32 v11, 1, v13
	v_add_u32_e32 v13, v16, v11
	ds_write_b16 v13, v8 offset:50688
	v_mul_f32_e32 v4, v9, v4
	v_cvt_pk_bf16_f32 v4, v4, v113
	ds_read_b32 v8, v14 offset:33796
	ds_read_b32 v9, v10 offset:17416
	v_add3_u32 v13, 0, v11, v3
	ds_write_b16 v13, v4 offset:59904
	s_waitcnt lgkmcnt(1)
	v_sub_f32_e32 v8, v8, v9
	v_mul_f32_e32 v8, 0x3fb8aa3b, v8
	v_exp_f32_e32 v8, v8
	v_lshlrev_b32_e32 v9, 16, v5
	v_and_b32_e32 v5, 0xffff0000, v5
	v_mul_f32_e32 v4, v8, v9
	v_cvt_pk_bf16_f32 v4, v4, v113
	ds_read_b32 v8, v14 offset:34056
	ds_read_b32 v11, v10 offset:34056
	ds_write_b16 v13, v4 offset:50832
	s_waitcnt lgkmcnt(1)
	v_sub_f32_e32 v8, v8, v11
	v_mul_f32_e32 v8, 0x3fb8aa3b, v8
	v_exp_f32_e32 v8, v8
	s_nop 0
	v_mul_f32_e32 v4, v8, v9
	v_cvt_pk_bf16_f32 v4, v4, v113
	ds_read_b32 v8, v14 offset:33800
	ds_read_b32 v9, v10 offset:17420
	ds_write_b16 v13, v4 offset:60048
	s_waitcnt lgkmcnt(1)
	v_sub_f32_e32 v8, v8, v9
	v_mul_f32_e32 v8, 0x3fb8aa3b, v8
	v_exp_f32_e32 v8, v8
	s_nop 0
	v_mul_f32_e32 v4, v8, v5
	v_cvt_pk_bf16_f32 v4, v4, v113
	ds_read_b32 v8, v14 offset:34060
	ds_read_b32 v9, v10 offset:34060
	ds_write_b16 v13, v4 offset:50976
	s_waitcnt lgkmcnt(1)
	v_sub_f32_e32 v8, v8, v9
	v_mul_f32_e32 v8, 0x3fb8aa3b, v8
	v_exp_f32_e32 v8, v8
	s_nop 0
	v_mul_f32_e32 v4, v8, v5
	v_cvt_pk_bf16_f32 v4, v4, v113
	ds_read_b32 v5, v14 offset:33804
	ds_read_b32 v8, v10 offset:17424
	ds_write_b16 v13, v4 offset:60192
	s_waitcnt lgkmcnt(1)
	v_sub_f32_e32 v5, v5, v8
	v_mul_f32_e32 v5, 0x3fb8aa3b, v5
	v_exp_f32_e32 v5, v5
	v_lshlrev_b32_e32 v8, 16, v6
	v_and_b32_e32 v6, 0xffff0000, v6
	v_mul_f32_e32 v4, v5, v8
	v_cvt_pk_bf16_f32 v4, v4, v113
	ds_read_b32 v5, v14 offset:34064
	ds_read_b32 v9, v10 offset:34064
	ds_write_b16 v13, v4 offset:51120
	s_waitcnt lgkmcnt(1)
	v_sub_f32_e32 v5, v5, v9
	v_mul_f32_e32 v5, 0x3fb8aa3b, v5
	v_exp_f32_e32 v5, v5
	s_nop 0
	v_mul_f32_e32 v4, v5, v8
	v_cvt_pk_bf16_f32 v4, v4, v113
	ds_read_b32 v5, v14 offset:33808
	ds_read_b32 v8, v10 offset:17428
	ds_write_b16 v13, v4 offset:60336
	s_waitcnt lgkmcnt(1)
	v_sub_f32_e32 v5, v5, v8
	v_mul_f32_e32 v5, 0x3fb8aa3b, v5
	v_exp_f32_e32 v5, v5
	s_nop 0
	v_mul_f32_e32 v4, v5, v6
	v_cvt_pk_bf16_f32 v4, v4, v113
	ds_read_b32 v5, v14 offset:34068
	ds_read_b32 v8, v10 offset:34068
	ds_write_b16 v13, v4 offset:51264
	s_waitcnt lgkmcnt(1)
	v_sub_f32_e32 v5, v5, v8
	v_mul_f32_e32 v5, 0x3fb8aa3b, v5
	v_exp_f32_e32 v5, v5
	s_nop 0
	v_mul_f32_e32 v4, v5, v6
	v_cvt_pk_bf16_f32 v4, v4, v113
	ds_read_b32 v5, v14 offset:33812
	ds_read_b32 v6, v10 offset:17432
	ds_write_b16 v13, v4 offset:60480
	s_waitcnt lgkmcnt(1)
	v_sub_f32_e32 v5, v5, v6
	v_mul_f32_e32 v5, 0x3fb8aa3b, v5
	v_exp_f32_e32 v5, v5
	v_lshlrev_b32_e32 v6, 16, v7
	v_mul_f32_e32 v4, v5, v6
	v_cvt_pk_bf16_f32 v4, v4, v113
	ds_read_b32 v5, v14 offset:34072
	ds_read_b32 v8, v10 offset:34072
	ds_write_b16 v13, v4 offset:51408
	s_waitcnt lgkmcnt(1)
	v_sub_f32_e32 v5, v5, v8
	v_mul_f32_e32 v5, 0x3fb8aa3b, v5
	v_exp_f32_e32 v5, v5
	s_nop 0
	v_mul_f32_e32 v4, v5, v6
	v_cvt_pk_bf16_f32 v4, v4, v113
	ds_read_b32 v5, v14 offset:33816
	ds_read_b32 v6, v10 offset:17436
	ds_write_b16 v13, v4 offset:60624
	s_waitcnt lgkmcnt(1)
	v_sub_f32_e32 v5, v5, v6
	v_mul_f32_e32 v5, 0x3fb8aa3b, v5
	v_exp_f32_e32 v5, v5
	v_and_b32_e32 v6, 0xffff0000, v7
	v_mul_f32_e32 v4, v5, v6
	v_cvt_pk_bf16_f32 v7, v4, v113
	ds_read_b32 v4, v14 offset:34076
	ds_read_b32 v5, v10 offset:34076
	ds_write_b16 v13, v7 offset:51552
	s_waitcnt lgkmcnt(1)
	v_sub_f32_e32 v4, v4, v5
	v_mul_f32_e32 v4, 0x3fb8aa3b, v4
	v_exp_f32_e32 v8, v4
	v_add_co_u32_e32 v4, vcc, s20, v0
	v_mul_f32_e32 v6, v8, v6
	s_nop 0
	v_addc_co_u32_e32 v5, vcc, 0, v1, vcc
	v_cvt_pk_bf16_f32 v14, v6, v113
	v_mov_b32_e32 v4, v216
	v_mov_b32_e32 v5, v217
	v_mov_b32_e32 v6, v218
	v_mov_b32_e32 v7, v219
	v_lshl_add_u64 v[0:1], v[0:1], 0, s[0:1]
	v_mov_b32_e32 v8, v220
	v_mov_b32_e32 v9, v221
	v_mov_b32_e32 v10, v222
	v_mov_b32_e32 v11, v223
	v_mul_u32_u24_e32 v1, 0x900, v12
	v_readlane_b32 s0, v253, 19
	ds_write_b16 v13, v14 offset:60768
	v_ashrrev_i32_e32 v0, 6, v22
	v_add3_u32 v1, s0, v3, v1
	s_movk_i32 s0, 0x80
	v_cmp_gt_i32_e32 vcc, s0, v22
	s_nop 0
	v_lshlrev_b32_e32 v3, 16, v4
	v_cvt_pk_bf16_f32 v3, v3, v113
	v_and_b32_e32 v4, 0xffff0000, v4
	ds_write_b16 v1, v3
	v_cvt_pk_bf16_f32 v3, v4, v113
	v_lshlrev_b32_e32 v12, 16, v5
	ds_write_b16 v1, v3 offset:144
	v_cvt_pk_bf16_f32 v3, v12, v113
	v_and_b32_e32 v5, 0xffff0000, v5
	ds_write_b16 v1, v3 offset:288
	v_cvt_pk_bf16_f32 v3, v5, v113
	v_lshlrev_b32_e32 v13, 16, v6
	ds_write_b16 v1, v3 offset:432
	v_cvt_pk_bf16_f32 v3, v13, v113
	v_and_b32_e32 v6, 0xffff0000, v6
	ds_write_b16 v1, v3 offset:576
	v_cvt_pk_bf16_f32 v3, v6, v113
	v_lshlrev_b32_e32 v14, 16, v7
	ds_write_b16 v1, v3 offset:720
	v_cvt_pk_bf16_f32 v3, v14, v113
	v_and_b32_e32 v7, 0xffff0000, v7
	ds_write_b16 v1, v3 offset:864
	v_cvt_pk_bf16_f32 v3, v7, v113
	s_nop 0
	v_lshlrev_b32_e32 v15, 16, v8
	ds_write_b16 v1, v3 offset:1008
	v_cvt_pk_bf16_f32 v3, v15, v113
	v_and_b32_e32 v8, 0xffff0000, v8
	ds_write_b16 v1, v3 offset:1152
	v_cvt_pk_bf16_f32 v3, v8, v113
	v_lshlrev_b32_e32 v16, 16, v9
	ds_write_b16 v1, v3 offset:1296
	v_cvt_pk_bf16_f32 v3, v16, v113
	v_and_b32_e32 v9, 0xffff0000, v9
	ds_write_b16 v1, v3 offset:1440
	v_cvt_pk_bf16_f32 v3, v9, v113
	v_lshlrev_b32_e32 v17, 16, v10
	ds_write_b16 v1, v3 offset:1584
	v_cvt_pk_bf16_f32 v3, v17, v113
	v_and_b32_e32 v10, 0xffff0000, v10
	ds_write_b16 v1, v3 offset:1728
	v_cvt_pk_bf16_f32 v3, v10, v113
	v_lshlrev_b32_e32 v18, 16, v11
	ds_write_b16 v1, v3 offset:1872
	v_cvt_pk_bf16_f32 v3, v18, v113
	v_and_b32_e32 v11, 0xffff0000, v11
	ds_write_b16 v1, v3 offset:2016
	v_cvt_pk_bf16_f32 v3, v11, v113
	ds_write_b16 v1, v3 offset:2160
	s_and_saveexec_b64 s[0:1], vcc
	s_cbranch_execz .LBB0_379
	v_cmp_gt_u32_e32 vcc, 64, v22
	v_and_b32_e32 v112, 0xfc, v2
	s_lshl_b64 s[2:3], s[4:5], 9
	v_cndmask_b32_e32 v1, v128, v129, vcc
	v_add3_u32 v1, 0, v112, v1
	ds_read_b32 v2, v1 offset:17408
	v_ashrrev_i32_e32 v1, 31, v0
	s_add_u32 s2, s44, s2
	s_addc_u32 s3, s45, s3
	s_waitcnt lgkmcnt(0)
	v_mul_f32_e32 v2, 0x3fb8aa3b, v2
	v_exp_f32_e32 v4, v2
	v_lshlrev_b64 v[2:3], 8, v[0:1]
	v_lshl_add_u64 v[2:3], s[2:3], 0, v[2:3]
	v_lshl_add_u64 v[2:3], v[2:3], 0, v[112:113]
	global_store_dword v[2:3], v4, off

.LBB0_1061:
	s_andn2_b64 vcc, exec, s[0:1]
	s_cbranch_vccnz .LBB0_1090
	s_add_i32 s4, s96, 0xfffffc00
	s_lshl_b32 s0, s4, 3
	v_mov_b32_e32 v22, v180
	s_and_b32 s9, s0, 0x7fffffc0
	v_mov_b32_e32 v0, v180
	s_movk_i32 s0, 0x800
	s_mov_b32 s14, s24
	s_and_b32 s8, s96, 7
	s_nop 0
	v_cmp_gt_i32_e32 vcc, s0, v0
	v_and_b32_e32 v6, 63, v0
	s_and_saveexec_b64 s[0:1], vcc
	v_readlane_b32 s68, v254, 12
	v_readlane_b32 s69, v254, 13
	v_readlane_b32 s70, v254, 14
	v_readlane_b32 s71, v254, 15
	v_readlane_b32 s72, v254, 16
	v_readlane_b32 s73, v254, 17
	v_readlane_b32 s74, v254, 18
	v_readlane_b32 s75, v254, 19
	v_readlane_b32 s76, v254, 20
	v_readlane_b32 s77, v254, 21
	v_readlane_b32 s78, v254, 22
	v_readlane_b32 s79, v254, 23
	v_readlane_b32 s80, v254, 24
	v_readlane_b32 s81, v254, 25
	v_readlane_b32 s82, v254, 26
	v_readlane_b32 s83, v254, 27
	s_cbranch_execz .LBB0_1074
	v_lshl_add_u32 v1, v0, 2, 0
	v_readlane_b32 s6, v254, 18
	v_readlane_b32 s7, v254, 19
	v_lshrrev_b32_e32 v2, 5, v0
	v_add_u32_e32 v2, s9, v2
	v_and_b32_e32 v7, 31, v0
	v_mov_b64_e32 v[4:5], s[6:7]
	v_mad_i64_i32 v[8:9], s[12:13], v2, s97, v[4:5]
	v_lshlrev_b32_e32 v10, 1, v7
	v_add_u32_e32 v10, 0x5000, v10
	v_mov_b32_e32 v11, 0
	s_mov_b32 s10, 0x50400
	s_mov_b32 s11, 0
	v_lshl_add_u64 v[8:9], v[8:9], 0, v[10:11]
	global_load_ushort v12, v[8:9], off
	v_lshl_add_u64 v[8:9], v[8:9], 0, s[10:11]
	global_load_ushort v13, v[8:9], off
	v_lshl_add_u64 v[8:9], v[8:9], 0, s[10:11]
	global_load_ushort v14, v[8:9], off
	v_lshl_add_u64 v[8:9], v[8:9], 0, s[10:11]
	global_load_ushort v15, v[8:9], off
	v_lshrrev_b32_e32 v16, 6, v0
	v_lshlrev_b32_e32 v2, 9, v16
	v_lshlrev_b32_e32 v16, 11, v16
	v_lshl_add_u32 v16, v6, 2, v16
	s_lshl_b32 s12, s8, 8
	v_add_u32_e32 v16, s12, v16
	v_add_u32_e32 v16, 0x10000, v16
	global_load_dword v18, v16, s[26:27]
	v_add_u32_e32 v17, 0x4000, v16
	global_load_dword v19, v17, s[26:27]
	v_add_u32_e32 v17, 0x8000, v16
	global_load_dword v20, v17, s[26:27]
	v_add_u32_e32 v17, 0xc000, v16
	global_load_dword v21, v17, s[26:27]
	v_lshrrev_b32_e32 v26, 3, v0
	v_add_u32_e32 v26, s9, v26
	v_mad_i64_i32 v[24:25], s[12:13], v26, s97, v[4:5]
	v_and_b32_e32 v27, 7, v0
	v_lshlrev_b32_e32 v28, 4, v27
	s_lshl_b32 s12, s8, 7
	v_add_u32_e32 v28, s12, v28
	v_add_u32_e32 v28, 0x1400, v28
	v_mov_b32_e32 v29, 0
	v_lshl_add_u64 v[30:31], v[24:25], 0, v[28:29]
	global_load_dwordx4 v[212:215], v[30:31], off
	v_lshlrev_b32_e32 v28, 5, v27
	s_lshl_b32 s12, s8, 8
	v_add_u32_e32 v28, s12, v28
	v_add_u32_e32 v28, 0x1800, v28
	v_lshl_add_u64 v[30:31], v[24:25], 0, v[28:29]
	global_load_dwordx4 v[216:219], v[30:31], off
	global_load_dwordx4 v[220:223], v[30:31], off offset:16
	s_lshl_b32 s12, s8, 6
	v_or3_b32 v2, v2, s12, v6
	v_add_u32_e32 v2, 0x400, v2
	s_movk_i32 s12, 0x80
	v_cmp_gt_u32_e64 s[12:13], s12, v0
	v_lshlrev_b32_e32 v2, 2, v2
	s_nop 1
	v_cndmask_b32_e64 v2, 0, v2, s[12:13]
	global_load_dword v3, v2, s[28:29]
	s_waitcnt vmcnt(0)
	v_lshlrev_b32_e32 v12, 16, v12
	v_lshlrev_b32_e32 v13, 16, v13
	v_lshlrev_b32_e32 v14, 16, v14
	v_lshlrev_b32_e32 v15, 16, v15
	ds_write2st64_b32 v1, v12, v13 offset1:8
	ds_write2st64_b32 v1, v14, v15 offset0:16 offset1:24
	ds_write2st64_b32 v1, v18, v19 offset0:32 offset1:40
	ds_write2st64_b32 v1, v20, v21 offset0:48 offset1:56
	s_and_saveexec_b64 s[2:3], s[12:13]
	ds_write_b32 v1, v3 offset:16384
	s_mov_b64 exec, s[2:3]

.LBB0_1087:
	s_or_b64 exec, exec, s[0:1]
	v_readlane_b32 s68, v254, 12
	v_ashrrev_i32_e32 v3, 3, v22
	v_readlane_b32 s74, v254, 18
	v_readlane_b32 s75, v254, 19
	v_add_u32_e32 v4, s9, v3
	v_and_b32_e32 v12, 7, v22
	v_mov_b64_e32 v[0:1], s[74:75]
	v_mad_i64_i32 v[0:1], s[0:1], v4, s97, v[0:1]
	s_lshl_b32 s24, s8, 7
	v_lshl_add_u64 v[4:5], v[0:1], 0, s[24:25]
	v_lshlrev_b32_e32 v112, 4, v12
	v_lshl_add_u64 v[4:5], v[4:5], 0, v[112:113]
	v_add_co_u32_e32 v4, vcc, 0x1000, v4
	v_lshlrev_b32_e32 v112, 5, v12
	s_nop 0
	v_addc_co_u32_e32 v5, vcc, 0, v5, vcc
	v_mov_b32_e32 v4, v212
	v_mov_b32_e32 v5, v213
	v_mov_b32_e32 v6, v214
	v_mov_b32_e32 v7, v215
	v_add_u32_e32 v8, 0, v112
	v_mad_u64_u32 v[10:11], s[0:1], v3, s11, v[8:9]
	ds_read_b32 v9, v8 offset:33788
	ds_read_b32 v11, v10 offset:17408
	v_lshlrev_b32_e32 v3, 1, v3
	v_mul_u32_u24_e32 v15, 0x240, v12
	v_add_u32_e32 v16, 0, v3
	s_movk_i32 s0, 0x460
	s_waitcnt lgkmcnt(0)
	v_sub_f32_e32 v9, v9, v11
	v_mul_f32_e32 v9, 0x3fb8aa3b, v9
	v_exp_f32_e32 v9, v9
	v_lshl_add_u32 v15, v15, 1, v16
	s_lshl_b32 s24, s8, 8
	v_lshl_add_u64 v[0:1], v[0:1], 0, s[24:25]
	v_lshl_add_u64 v[0:1], v[0:1], 0, v[112:113]
	v_readlane_b32 s69, v254, 13
	v_readlane_b32 s70, v254, 14
	v_readlane_b32 s71, v254, 15
	v_readlane_b32 s72, v254, 16
	v_readlane_b32 s73, v254, 17
	v_readlane_b32 s76, v254, 20
	v_readlane_b32 s77, v254, 21
	v_readlane_b32 s78, v254, 22
	v_readlane_b32 s79, v254, 23
	v_readlane_b32 s80, v254, 24
	v_readlane_b32 s81, v254, 25
	v_readlane_b32 s82, v254, 26
	v_readlane_b32 s83, v254, 27
	s_nop 0
	v_lshlrev_b32_e32 v11, 16, v4
	v_mul_f32_e32 v9, v9, v11
	v_cvt_pk_bf16_f32 v9, v9, v113
	ds_read_b32 v13, v8 offset:34048
	ds_read_b32 v14, v10 offset:34048
	v_mad_u32_u24 v8, v12, s0, v8
	s_movk_i32 s0, 0xfba0
	ds_write_b16 v15, v9 offset:50688
	v_and_b32_e32 v4, 0xffff0000, v4
	s_waitcnt lgkmcnt(1)
	v_sub_f32_e32 v13, v13, v14
	v_mul_f32_e32 v13, 0x3fb8aa3b, v13
	v_exp_f32_e32 v13, v13
	v_mad_i32_i24 v14, v12, s0, v8
	v_add_u32_e32 v8, v8, v3
	s_movk_i32 s0, 0x1000
	v_mul_f32_e32 v9, v13, v11
	v_cvt_pk_bf16_f32 v9, v9, v113
	ds_read_b32 v11, v14 offset:33792
	ds_read_b32 v13, v10 offset:17412
	ds_write_b16 v8, v9 offset:59904
	s_waitcnt lgkmcnt(1)
	v_sub_f32_e32 v11, v11, v13
	v_mul_f32_e32 v11, 0x3fb8aa3b, v11
	v_exp_f32_e32 v11, v11
	v_lshl_or_b32 v13, v12, 3, 1
	v_mul_u32_u24_e32 v13, 0x48, v13
	v_mul_f32_e32 v8, v11, v4
	v_cvt_pk_bf16_f32 v8, v8, v113
	ds_read_b32 v9, v14 offset:34052
	ds_read_b32 v11, v10 offset:34052
	s_waitcnt lgkmcnt(0)
	v_sub_f32_e32 v9, v9, v11
	v_mul_f32_e32 v9, 0x3fb8aa3b, v9
	v_exp_f32_e32 v9, v9
	v_lshlrev_b32_e32 v11, 1, v13
	v_add_u32_e32 v13, v16, v11
	ds_write_b16 v13, v8 offset:50688
	v_mul_f32_e32 v4, v9, v4
	v_cvt_pk_bf16_f32 v4, v4, v113
	ds_read_b32 v8, v14 offset:33796
	ds_read_b32 v9, v10 offset:17416
	v_add3_u32 v13, 0, v11, v3
	ds_write_b16 v13, v4 offset:59904
	s_waitcnt lgkmcnt(1)
	v_sub_f32_e32 v8, v8, v9
	v_mul_f32_e32 v8, 0x3fb8aa3b, v8
	v_exp_f32_e32 v8, v8
	v_lshlrev_b32_e32 v9, 16, v5
	v_and_b32_e32 v5, 0xffff0000, v5
	v_mul_f32_e32 v4, v8, v9
	v_cvt_pk_bf16_f32 v4, v4, v113
	ds_read_b32 v8, v14 offset:34056
	ds_read_b32 v11, v10 offset:34056
	ds_write_b16 v13, v4 offset:50832
	s_waitcnt lgkmcnt(1)
	v_sub_f32_e32 v8, v8, v11
	v_mul_f32_e32 v8, 0x3fb8aa3b, v8
	v_exp_f32_e32 v8, v8
	s_nop 0
	v_mul_f32_e32 v4, v8, v9
	v_cvt_pk_bf16_f32 v4, v4, v113
	ds_read_b32 v8, v14 offset:33800
	ds_read_b32 v9, v10 offset:17420
	ds_write_b16 v13, v4 offset:60048
	s_waitcnt lgkmcnt(1)
	v_sub_f32_e32 v8, v8, v9
	v_mul_f32_e32 v8, 0x3fb8aa3b, v8
	v_exp_f32_e32 v8, v8
	s_nop 0
	v_mul_f32_e32 v4, v8, v5
	v_cvt_pk_bf16_f32 v4, v4, v113
	ds_read_b32 v8, v14 offset:34060
	ds_read_b32 v9, v10 offset:34060
	ds_write_b16 v13, v4 offset:50976
	s_waitcnt lgkmcnt(1)
	v_sub_f32_e32 v8, v8, v9
	v_mul_f32_e32 v8, 0x3fb8aa3b, v8
	v_exp_f32_e32 v8, v8
	s_nop 0
	v_mul_f32_e32 v4, v8, v5
	v_cvt_pk_bf16_f32 v4, v4, v113
	ds_read_b32 v5, v14 offset:33804
	ds_read_b32 v8, v10 offset:17424
	ds_write_b16 v13, v4 offset:60192
	s_waitcnt lgkmcnt(1)
	v_sub_f32_e32 v5, v5, v8
	v_mul_f32_e32 v5, 0x3fb8aa3b, v5
	v_exp_f32_e32 v5, v5
	v_lshlrev_b32_e32 v8, 16, v6
	v_and_b32_e32 v6, 0xffff0000, v6
	v_mul_f32_e32 v4, v5, v8
	v_cvt_pk_bf16_f32 v4, v4, v113
	ds_read_b32 v5, v14 offset:34064
	ds_read_b32 v9, v10 offset:34064
	ds_write_b16 v13, v4 offset:51120
	s_waitcnt lgkmcnt(1)
	v_sub_f32_e32 v5, v5, v9
	v_mul_f32_e32 v5, 0x3fb8aa3b, v5
	v_exp_f32_e32 v5, v5
	s_nop 0
	v_mul_f32_e32 v4, v5, v8
	v_cvt_pk_bf16_f32 v4, v4, v113
	ds_read_b32 v5, v14 offset:33808
	ds_read_b32 v8, v10 offset:17428
	ds_write_b16 v13, v4 offset:60336
	s_waitcnt lgkmcnt(1)
	v_sub_f32_e32 v5, v5, v8
	v_mul_f32_e32 v5, 0x3fb8aa3b, v5
	v_exp_f32_e32 v5, v5
	s_nop 0
	v_mul_f32_e32 v4, v5, v6
	v_cvt_pk_bf16_f32 v4, v4, v113
	ds_read_b32 v5, v14 offset:34068
	ds_read_b32 v8, v10 offset:34068
	ds_write_b16 v13, v4 offset:51264
	s_waitcnt lgkmcnt(1)
	v_sub_f32_e32 v5, v5, v8
	v_mul_f32_e32 v5, 0x3fb8aa3b, v5
	v_exp_f32_e32 v5, v5
	s_nop 0
	v_mul_f32_e32 v4, v5, v6
	v_cvt_pk_bf16_f32 v4, v4, v113
	ds_read_b32 v5, v14 offset:33812
	ds_read_b32 v6, v10 offset:17432
	ds_write_b16 v13, v4 offset:60480
	s_waitcnt lgkmcnt(1)
	v_sub_f32_e32 v5, v5, v6
	v_mul_f32_e32 v5, 0x3fb8aa3b, v5
	v_exp_f32_e32 v5, v5
	v_lshlrev_b32_e32 v6, 16, v7
	v_mul_f32_e32 v4, v5, v6
	v_cvt_pk_bf16_f32 v4, v4, v113
	ds_read_b32 v5, v14 offset:34072
	ds_read_b32 v8, v10 offset:34072
	ds_write_b16 v13, v4 offset:51408
	s_waitcnt lgkmcnt(1)
	v_sub_f32_e32 v5, v5, v8
	v_mul_f32_e32 v5, 0x3fb8aa3b, v5
	v_exp_f32_e32 v5, v5
	s_nop 0
	v_mul_f32_e32 v4, v5, v6
	v_cvt_pk_bf16_f32 v4, v4, v113
	ds_read_b32 v5, v14 offset:33816
	ds_read_b32 v6, v10 offset:17436
	ds_write_b16 v13, v4 offset:60624
	s_waitcnt lgkmcnt(1)
	v_sub_f32_e32 v5, v5, v6
	v_mul_f32_e32 v5, 0x3fb8aa3b, v5
	v_exp_f32_e32 v5, v5
	v_and_b32_e32 v6, 0xffff0000, v7
	v_mul_f32_e32 v4, v5, v6
	v_cvt_pk_bf16_f32 v7, v4, v113
	ds_read_b32 v4, v14 offset:34076
	ds_read_b32 v5, v10 offset:34076
	ds_write_b16 v13, v7 offset:51552
	s_waitcnt lgkmcnt(1)
	v_sub_f32_e32 v4, v4, v5
	v_mul_f32_e32 v4, 0x3fb8aa3b, v4
	v_exp_f32_e32 v8, v4
	v_add_co_u32_e32 v4, vcc, s0, v0
	s_mov_b64 s[0:1], 0x1800
	s_nop 0
	v_addc_co_u32_e32 v5, vcc, 0, v1, vcc
	v_mul_f32_e32 v6, v8, v6
	v_cvt_pk_bf16_f32 v14, v6, v113
	v_mov_b32_e32 v4, v216
	v_mov_b32_e32 v5, v217
	v_mov_b32_e32 v6, v218
	v_mov_b32_e32 v7, v219
	v_lshl_add_u64 v[0:1], v[0:1], 0, s[0:1]
	v_mov_b32_e32 v8, v220
	v_mov_b32_e32 v9, v221
	v_mov_b32_e32 v10, v222
	v_mov_b32_e32 v11, v223
	v_mul_u32_u24_e32 v1, 0x900, v12
	v_readlane_b32 s0, v253, 25
	ds_write_b16 v13, v14 offset:60768
	v_ashrrev_i32_e32 v0, 6, v22
	v_add3_u32 v1, s0, v3, v1
	s_movk_i32 s0, 0x80
	v_cmp_gt_i32_e32 vcc, s0, v22
	s_nop 0
	v_lshlrev_b32_e32 v3, 16, v4
	v_cvt_pk_bf16_f32 v3, v3, v113
	v_and_b32_e32 v4, 0xffff0000, v4
	ds_write_b16 v1, v3
	v_cvt_pk_bf16_f32 v3, v4, v113
	v_lshlrev_b32_e32 v12, 16, v5
	ds_write_b16 v1, v3 offset:144
	v_cvt_pk_bf16_f32 v3, v12, v113
	v_and_b32_e32 v5, 0xffff0000, v5
	ds_write_b16 v1, v3 offset:288
	v_cvt_pk_bf16_f32 v3, v5, v113
	v_lshlrev_b32_e32 v13, 16, v6
	ds_write_b16 v1, v3 offset:432
	v_cvt_pk_bf16_f32 v3, v13, v113
	v_and_b32_e32 v6, 0xffff0000, v6
	ds_write_b16 v1, v3 offset:576
	v_cvt_pk_bf16_f32 v3, v6, v113
	v_lshlrev_b32_e32 v14, 16, v7
	ds_write_b16 v1, v3 offset:720
	v_cvt_pk_bf16_f32 v3, v14, v113
	v_and_b32_e32 v7, 0xffff0000, v7
	ds_write_b16 v1, v3 offset:864
	v_cvt_pk_bf16_f32 v3, v7, v113
	s_nop 0
	v_lshlrev_b32_e32 v15, 16, v8
	ds_write_b16 v1, v3 offset:1008
	v_cvt_pk_bf16_f32 v3, v15, v113
	v_and_b32_e32 v8, 0xffff0000, v8
	ds_write_b16 v1, v3 offset:1152
	v_cvt_pk_bf16_f32 v3, v8, v113
	v_lshlrev_b32_e32 v16, 16, v9
	ds_write_b16 v1, v3 offset:1296
	v_cvt_pk_bf16_f32 v3, v16, v113
	v_and_b32_e32 v9, 0xffff0000, v9
	ds_write_b16 v1, v3 offset:1440
	v_cvt_pk_bf16_f32 v3, v9, v113
	v_lshlrev_b32_e32 v17, 16, v10
	ds_write_b16 v1, v3 offset:1584
	v_cvt_pk_bf16_f32 v3, v17, v113
	v_and_b32_e32 v10, 0xffff0000, v10
	ds_write_b16 v1, v3 offset:1728
	v_cvt_pk_bf16_f32 v3, v10, v113
	v_lshlrev_b32_e32 v18, 16, v11
	ds_write_b16 v1, v3 offset:1872
	v_cvt_pk_bf16_f32 v3, v18, v113
	v_and_b32_e32 v11, 0xffff0000, v11
	ds_write_b16 v1, v3 offset:2016
	v_cvt_pk_bf16_f32 v3, v11, v113
	ds_write_b16 v1, v3 offset:2160
	s_and_saveexec_b64 s[0:1], vcc
	s_cbranch_execz .LBB0_1089
	v_cmp_gt_u32_e32 vcc, 64, v22
	v_and_b32_e32 v112, 0xfc, v2
	s_lshl_b64 s[2:3], s[4:5], 9
	v_cndmask_b32_e32 v1, v128, v129, vcc
	v_add3_u32 v1, 0, v112, v1
	ds_read_b32 v2, v1 offset:17408
	v_ashrrev_i32_e32 v1, 31, v0
	s_add_u32 s2, s44, s2
	s_addc_u32 s3, s45, s3
	s_waitcnt lgkmcnt(0)
	v_mul_f32_e32 v2, 0x3fb8aa3b, v2
	v_exp_f32_e32 v4, v2
	v_lshlrev_b64 v[2:3], 8, v[0:1]
	v_lshl_add_u64 v[2:3], s[2:3], 0, v[2:3]
	v_lshl_add_u64 v[2:3], v[2:3], 0, v[112:113]
	global_store_dword v[2:3], v4, off
